# adds: attention epilogue cross-half sums via v_permlane32_swap instead of ds_bpermute round trips
# baseline (speedup 1.0000x reference)
; #define LAS __attribute__((address_space(3)))
; __device__ __forceinline__ int crow(int r, int hi) { return (r & 3) + 8 * (r >> 2) + 4 * hi; }
; __device__ __forceinline__ void attn_unit(const bf16* Hb, const bf16* KD, const bf16* VD, bf16* MIX, int row0, int S, int head, int qb, float lam, const float* dng, float kn0, float kn1, LAS unsigned char* lds, int wave_u) {
;     ...
;     if (fast) l = l2.x + l2.y;
;     l += __shfl_xor(l, 32);
;     const float rl = 1.f / l;
;     LAS float* X = (LAS float*)lds;
;     if (c == 1) {
;         const float f = rl * lam;
; #pragma unroll
;         for (int b = 0; b < 4; ++b)
; #pragma unroll
;             for (int r = 0; r < 16; ++r) X[(qs * 32 + r32e) * XS + 32 * b + crow(r, hhe)] = o[b][r] * f;
;     }
;     __syncthreads();
;     if (c == 0) {
;         float ss = 0.f;
; #pragma unroll
;         for (int b = 0; b < 4; ++b)
; #pragma unroll
;             for (int r = 0; r < 16; ++r) { const float v = o[b][r] * rl - X[(qs * 32 + r32e) * XS + 32 * b + crow(r, hhe)]; o[b][r] = v; ss += v * v; }
;         ss += __shfl_xor(ss, 32);
.LBB0_677:
	v_add_f32_e32 v0, v154, v155
	v_cndmask_b32_e64 v0, v215, v0, s[36:37]
	v_mov_b32_e32 v66, v0
	s_nop 1
	v_permlane32_swap_b32_e32 v66, v0
	v_mbcnt_lo_u32_b32 v67, -1, 0
	v_mbcnt_hi_u32_b32 v67, -1, v67
	s_cmp_lg_u32 s72, 1
	v_and_b32_e32 v79, 31, v67
	v_bfe_u32 v67, v67, 5, 1
	s_waitcnt lgkmcnt(0)
	v_add_f32_e32 v0, v0, v66
	v_div_scale_f32 v66, s[0:1], v0, v0, 1.0
	v_rcp_f32_e32 v68, v66
	v_div_scale_f32 v69, vcc, 1.0, v0, 1.0
	v_fma_f32 v70, -v66, v68, 1.0
	v_fmac_f32_e32 v68, v70, v68
	v_mul_f32_e32 v70, v69, v68
	v_fma_f32 v71, -v66, v70, v69
	v_fmac_f32_e32 v70, v71, v68
	v_fma_f32 v66, -v66, v70, v69
	v_div_fmas_f32 v66, v66, v68, v70
	v_div_fixup_f32 v0, v66, v0, 1.0
	v_lshlrev_b32_e32 v66, 4, v67
	s_cbranch_scc1 .LBB0_679
	v_or_b32_e32 v68, s71, v79
	v_mul_u32_u24_e32 v68, 0x210, v68
	v_mul_f32_e32 v72, s4, v0
	v_add3_u32 v73, 0, v68, v66
	v_pk_mul_f32 v[68:69], v[50:51], v[72:73] op_sel_hi:[1,0]
	v_pk_mul_f32 v[70:71], v[52:53], v[72:73] op_sel_hi:[1,0]
	ds_write_b128 v73, v[68:71]
	v_pk_mul_f32 v[68:69], v[54:55], v[72:73] op_sel_hi:[1,0]
	v_pk_mul_f32 v[70:71], v[56:57], v[72:73] op_sel_hi:[1,0]
	ds_write_b128 v73, v[68:71] offset:32
	v_pk_mul_f32 v[68:69], v[58:59], v[72:73] op_sel_hi:[1,0]
	v_pk_mul_f32 v[70:71], v[60:61], v[72:73] op_sel_hi:[1,0]
	ds_write_b128 v73, v[68:71] offset:64
	v_pk_mul_f32 v[68:69], v[62:63], v[72:73] op_sel_hi:[1,0]
	v_pk_mul_f32 v[70:71], v[64:65], v[72:73] op_sel_hi:[1,0]
	ds_write_b128 v73, v[68:71] offset:96
	v_pk_mul_f32 v[68:69], v[34:35], v[72:73] op_sel_hi:[1,0]
	v_pk_mul_f32 v[70:71], v[36:37], v[72:73] op_sel_hi:[1,0]
	ds_write_b128 v73, v[68:71] offset:128
	v_pk_mul_f32 v[68:69], v[38:39], v[72:73] op_sel_hi:[1,0]
	v_pk_mul_f32 v[70:71], v[40:41], v[72:73] op_sel_hi:[1,0]
	ds_write_b128 v73, v[68:71] offset:160
	v_pk_mul_f32 v[68:69], v[42:43], v[72:73] op_sel_hi:[1,0]
	v_pk_mul_f32 v[70:71], v[44:45], v[72:73] op_sel_hi:[1,0]
	ds_write_b128 v73, v[68:71] offset:192
	v_pk_mul_f32 v[68:69], v[46:47], v[72:73] op_sel_hi:[1,0]
	v_pk_mul_f32 v[70:71], v[48:49], v[72:73] op_sel_hi:[1,0]
	ds_write_b128 v73, v[68:71] offset:224
	v_pk_mul_f32 v[68:69], v[18:19], v[72:73] op_sel_hi:[1,0]
	v_pk_mul_f32 v[70:71], v[20:21], v[72:73] op_sel_hi:[1,0]
	ds_write_b128 v73, v[68:71] offset:256
	v_pk_mul_f32 v[68:69], v[22:23], v[72:73] op_sel_hi:[1,0]
	v_pk_mul_f32 v[70:71], v[24:25], v[72:73] op_sel_hi:[1,0]
	ds_write_b128 v73, v[68:71] offset:288
	v_pk_mul_f32 v[68:69], v[26:27], v[72:73] op_sel_hi:[1,0]
	v_pk_mul_f32 v[70:71], v[28:29], v[72:73] op_sel_hi:[1,0]
	ds_write_b128 v73, v[68:71] offset:320
	v_pk_mul_f32 v[68:69], v[30:31], v[72:73] op_sel_hi:[1,0]
	v_pk_mul_f32 v[70:71], v[32:33], v[72:73] op_sel_hi:[1,0]
	ds_write_b128 v73, v[68:71] offset:352
	v_pk_mul_f32 v[68:69], v[2:3], v[72:73] op_sel_hi:[1,0]
	v_pk_mul_f32 v[70:71], v[4:5], v[72:73] op_sel_hi:[1,0]
	ds_write_b128 v73, v[68:71] offset:384
	v_pk_mul_f32 v[68:69], v[6:7], v[72:73] op_sel_hi:[1,0]
	v_pk_mul_f32 v[70:71], v[8:9], v[72:73] op_sel_hi:[1,0]
	ds_write_b128 v73, v[68:71] offset:416
	v_pk_mul_f32 v[68:69], v[10:11], v[72:73] op_sel_hi:[1,0]
	v_pk_mul_f32 v[70:71], v[12:13], v[72:73] op_sel_hi:[1,0]
	ds_write_b128 v73, v[68:71] offset:448
	v_pk_mul_f32 v[68:69], v[14:15], v[72:73] op_sel_hi:[1,0]
	v_pk_mul_f32 v[70:71], v[16:17], v[72:73] op_sel_hi:[1,0]
	ds_write_b128 v73, v[68:71] offset:480
.LBB0_679:
	s_andn2_b64 vcc, exec, s[34:35]
	s_waitcnt lgkmcnt(0)
	s_barrier
	s_cbranch_vccnz .LBB0_607
	v_or_b32_e32 v68, s70, v79
	s_movk_i32 s0, 0x210
	v_mul_lo_u32 v68, v68, s0
	v_add3_u32 v80, 0, v68, v66
	ds_read_b128 v[68:71], v80
	ds_read_b128 v[72:75], v80 offset:32
	ds_read_b128 v[82:85], v80 offset:288
	s_lshl_b32 s2, s69, 7
	s_lshl_b32 s4, s2, 1
	s_waitcnt lgkmcnt(2)
	v_fma_f32 v68, v50, v0, -v68
	v_fma_f32 v50, v51, v0, -v69
	v_fma_f32 v51, v52, v0, -v70
	v_fma_f32 v53, v53, v0, -v71
	s_waitcnt lgkmcnt(1)
	v_fma_f32 v69, v54, v0, -v72
	v_fma_f32 v55, v55, v0, -v73
	ds_read_b128 v[70:73], v80 offset:64
	v_mul_f32_e32 v81, v50, v50
	v_fmac_f32_e32 v81, v68, v68
	v_fma_f32 v56, v56, v0, -v74
	v_fma_f32 v57, v57, v0, -v75
	s_waitcnt lgkmcnt(0)
	v_fma_f32 v54, v60, v0, -v72
	v_fma_f32 v52, v61, v0, -v73
	ds_read_b128 v[72:75], v80 offset:96
	v_fmac_f32_e32 v81, v51, v51
	v_fmac_f32_e32 v81, v53, v53
	v_fmac_f32_e32 v81, v69, v69
	v_fmac_f32_e32 v81, v55, v55
	v_fmac_f32_e32 v81, v56, v56
	v_fma_f32 v70, v58, v0, -v70
	v_fma_f32 v58, v59, v0, -v71
	s_waitcnt lgkmcnt(0)
	v_fma_f32 v71, v62, v0, -v72
	v_fma_f32 v63, v63, v0, -v73
	v_fma_f32 v62, v64, v0, -v74
	v_fma_f32 v61, v65, v0, -v75
	ds_read_b128 v[72:75], v80 offset:128
	v_fmac_f32_e32 v81, v57, v57
	v_fmac_f32_e32 v81, v70, v70
	v_fmac_f32_e32 v81, v58, v58
	v_fmac_f32_e32 v81, v54, v54
	v_fmac_f32_e32 v81, v52, v52
	s_waitcnt lgkmcnt(0)
	v_fma_f32 v60, v34, v0, -v72
	v_fma_f32 v59, v35, v0, -v73
	v_fma_f32 v35, v36, v0, -v74
	v_fma_f32 v34, v37, v0, -v75
	ds_read_b128 v[72:75], v80 offset:160
	v_fmac_f32_e32 v81, v71, v71
	v_fmac_f32_e32 v81, v63, v63
	v_fmac_f32_e32 v81, v62, v62
	v_fmac_f32_e32 v81, v61, v61
	v_fmac_f32_e32 v81, v60, v60
	s_waitcnt lgkmcnt(0)
	v_fma_f32 v64, v40, v0, -v74
	v_fma_f32 v41, v41, v0, -v75
	ds_read_b128 v[74:77], v80 offset:192
	v_fmac_f32_e32 v81, v59, v59
	v_fmac_f32_e32 v81, v35, v35
	v_fmac_f32_e32 v81, v34, v34
	v_fma_f32 v72, v38, v0, -v72
	v_fmac_f32_e32 v81, v72, v72
	v_fma_f32 v65, v39, v0, -v73
	v_fmac_f32_e32 v81, v65, v65
	s_waitcnt lgkmcnt(0)
	v_fma_f32 v39, v42, v0, -v74
	v_fma_f32 v38, v43, v0, -v75
	v_fma_f32 v37, v44, v0, -v76
	v_fma_f32 v36, v45, v0, -v77
	ds_read_b128 v[74:77], v80 offset:224
	v_fmac_f32_e32 v81, v64, v64
	v_fmac_f32_e32 v81, v41, v41
	v_fmac_f32_e32 v81, v39, v39
	v_fmac_f32_e32 v81, v38, v38
	v_fmac_f32_e32 v81, v37, v37
	s_waitcnt lgkmcnt(0)
; __device__ __forceinline__ int crow(int r, int hi) { return (r & 3) + 8 * (r >> 2) + 4 * hi; }
; __device__ __forceinline__ void attn_unit(const bf16* Hb, const bf16* KD, const bf16* VD, bf16* MIX, int row0, int S, int head, int qb, float lam, const float* dng, float kn0, float kn1, LAS unsigned char* lds, int wave_u) {
;     ...
;         float ss = 0.f;
; #pragma unroll
;         for (int b = 0; b < 4; ++b)
; #pragma unroll
;             for (int r = 0; r < 16; ++r) { const float v = o[b][r] * rl - X[(qs * 32 + r32e) * XS + 32 * b + crow(r, hhe)]; o[b][r] = v; ss += v * v; }
;         ss += __shfl_xor(ss, 32);
;         const float rn = (1.f - LAM_INIT) / sqrtf(ss * (1.f / 128.f) + 1e-5f);
;         bf16* orow = MIX + (size_t)(row0 + q0 + r32e) * D + head * 128;
; #pragma unroll
;         for (int b = 0; b < 4; ++b)
; #pragma unroll
;             for (int rg = 0; rg < 4; ++rg) { const int d = 32 * b + 8 * rg + 4 * hhe; const f32x4 g4 = *(const f32x4*)(dng + d);
	v_fma_f32 v73, v46, v0, -v74
	v_fma_f32 v47, v47, v0, -v75
	v_fma_f32 v45, v48, v0, -v76
	v_fma_f32 v44, v49, v0, -v77
	ds_read_b128 v[74:77], v80 offset:256
	v_fmac_f32_e32 v81, v36, v36
	v_fmac_f32_e32 v81, v73, v73
	v_fmac_f32_e32 v81, v47, v47
	v_fmac_f32_e32 v81, v45, v45
	v_fmac_f32_e32 v81, v44, v44
	s_waitcnt lgkmcnt(0)
	v_fma_f32 v43, v18, v0, -v74
	v_fmac_f32_e32 v81, v43, v43
	v_fma_f32 v42, v19, v0, -v75
	v_fmac_f32_e32 v81, v42, v42
	v_fma_f32 v40, v20, v0, -v76
	v_fma_f32 v75, v22, v0, -v82
	v_fma_f32 v74, v23, v0, -v83
	v_fma_f32 v49, v24, v0, -v84
	v_fma_f32 v48, v25, v0, -v85
	ds_read_b128 v[82:85], v80 offset:352
	v_fmac_f32_e32 v81, v40, v40
	v_fma_f32 v20, v21, v0, -v77
	ds_read_b128 v[22:25], v80 offset:320
	v_fmac_f32_e32 v81, v20, v20
	v_fmac_f32_e32 v81, v75, v75
	v_fmac_f32_e32 v81, v74, v74
	v_fmac_f32_e32 v81, v49, v49
	s_waitcnt lgkmcnt(1)
	v_fma_f32 v78, v30, v0, -v82
	v_fma_f32 v77, v31, v0, -v83
	v_fma_f32 v76, v32, v0, -v84
	v_fma_f32 v33, v33, v0, -v85
	ds_read_b128 v[82:85], v80 offset:384
	v_fmac_f32_e32 v81, v48, v48
	s_waitcnt lgkmcnt(1)
	v_fma_f32 v46, v26, v0, -v22
	v_fmac_f32_e32 v81, v46, v46
	v_fma_f32 v26, v27, v0, -v23
	v_fmac_f32_e32 v81, v26, v26
	v_fma_f32 v23, v28, v0, -v24
	v_fmac_f32_e32 v81, v23, v23
	v_fma_f32 v22, v29, v0, -v25
	v_fmac_f32_e32 v81, v22, v22
	s_waitcnt lgkmcnt(0)
	v_fma_f32 v32, v2, v0, -v82
	v_fma_f32 v31, v3, v0, -v83
	v_fma_f32 v29, v4, v0, -v84
	v_fma_f32 v27, v5, v0, -v85
	ds_read_b128 v[2:5], v80 offset:416
	v_fmac_f32_e32 v81, v78, v78
	v_fmac_f32_e32 v81, v77, v77
	v_fmac_f32_e32 v81, v76, v76
	v_fmac_f32_e32 v81, v33, v33
	v_fmac_f32_e32 v81, v32, v32
	s_waitcnt lgkmcnt(0)
	v_fma_f32 v30, v6, v0, -v2
	v_fma_f32 v28, v7, v0, -v3
	v_fma_f32 v25, v8, v0, -v4
	v_fma_f32 v24, v9, v0, -v5
	ds_read_b128 v[2:5], v80 offset:448
	v_fmac_f32_e32 v81, v31, v31
	v_fmac_f32_e32 v81, v29, v29
	v_fmac_f32_e32 v81, v27, v27
	v_fmac_f32_e32 v81, v30, v30
	v_fmac_f32_e32 v81, v28, v28
	s_waitcnt lgkmcnt(0)
	v_fma_f32 v21, v10, v0, -v2
	v_fma_f32 v19, v11, v0, -v3
	v_fma_f32 v18, v12, v0, -v4
	v_fma_f32 v13, v13, v0, -v5
	ds_read_b128 v[2:5], v80 offset:480
	v_fmac_f32_e32 v81, v25, v25
	v_fmac_f32_e32 v81, v24, v24
	v_fmac_f32_e32 v81, v21, v21
	v_fmac_f32_e32 v81, v19, v19
	v_fmac_f32_e32 v81, v18, v18
	s_waitcnt lgkmcnt(0)
	v_pk_fma_f32 v[8:9], v[14:15], v[0:1], v[2:3] op_sel_hi:[1,0,1] neg_lo:[0,0,1] neg_hi:[0,0,1]
	v_fmac_f32_e32 v81, v13, v13
	v_pk_mul_f32 v[2:3], v[8:9], v[8:9]
	v_pk_fma_f32 v[6:7], v[16:17], v[0:1], v[4:5] op_sel_hi:[1,0,1] neg_lo:[0,0,1] neg_hi:[0,0,1]
	v_add_f32_e32 v2, v81, v2
	v_add_f32_e32 v10, v2, v3
	v_pk_mul_f32 v[2:3], v[6:7], v[6:7]
	s_nop 0
	v_add_f32_e32 v0, v10, v2
	v_add_f32_e32 v0, v0, v3
	v_mov_b32_e32 v2, v0
	s_nop 1
	v_permlane32_swap_b32_e32 v2, v0
	s_waitcnt lgkmcnt(0)
	v_add_f32_e32 v0, v0, v2
	v_fmamk_f32 v0, v0, 0x3c000000, v203
	v_cmp_gt_f32_e32 vcc, s50, v0
	v_mul_f32_e32 v2, 0x4f800000, v0
	s_nop 0
	v_cndmask_b32_e32 v0, v0, v2, vcc
	v_sqrt_f32_e32 v2, v0
	s_nop 0
	v_add_u32_e32 v3, -1, v2
	v_fma_f32 v4, -v3, v2, v0
	v_cmp_ge_f32_e64 s[0:1], 0, v4
	v_add_u32_e32 v4, 1, v2
	s_nop 0
	v_cndmask_b32_e64 v3, v2, v3, s[0:1]
	v_fma_f32 v2, -v4, v2, v0
	v_cmp_lt_f32_e64 s[0:1], 0, v2
	s_nop 1
	v_cndmask_b32_e64 v2, v3, v4, s[0:1]
	v_mul_f32_e32 v3, 0x37800000, v2
	v_cndmask_b32_e32 v2, v2, v3, vcc
	v_cmp_class_f32_e32 vcc, v0, v201
	s_nop 1
	v_cndmask_b32_e32 v0, v2, v0, vcc
	v_div_scale_f32 v2, s[0:1], v0, v0, s61
	v_rcp_f32_e32 v3, v2
	v_readlane_b32 s0, v253, 21
	v_readlane_b32 s1, v253, 22
	v_fma_f32 v4, -v2, v3, 1.0
	v_fmac_f32_e32 v3, v4, v3
	v_div_scale_f32 v4, vcc, s61, v0, s61
	v_mul_f32_e32 v5, v4, v3
	v_fma_f32 v10, -v2, v5, v4
	v_fmac_f32_e32 v5, v10, v3
	v_fma_f32 v2, -v2, v5, v4
	v_div_fmas_f32 v2, v2, v3, v5
	v_div_fixup_f32 v12, v2, v0, s61
	v_add_lshl_u32 v0, v79, s68, 11
	v_readlane_b32 s68, v251, 54
	v_lshl_add_u64 v[2:3], s[0:1], 0, v[0:1]
	v_readlane_b32 s69, v251, 55
	v_lshl_add_u64 v[10:11], v[2:3], 0, s[4:5]
	v_mul_f32_e32 v0, v68, v12
	v_readlane_b32 s70, v251, 56
	v_readlane_b32 s71, v251, 57
	v_readlane_b32 s72, v251, 58
	global_load_dwordx4 v[120:123], v66, s[68:69]
	global_load_dwordx4 v[124:127], v66, s[68:69] offset:32
	global_load_dwordx4 v[128:131], v66, s[68:69] offset:64
	global_load_dwordx4 v[132:135], v66, s[68:69] offset:96
	global_load_dwordx4 v[136:139], v66, s[68:69] offset:128
	global_load_dwordx4 v[140:143], v66, s[68:69] offset:160
	global_load_dwordx4 v[144:147], v66, s[68:69] offset:192
	global_load_dwordx4 v[148:151], v66, s[68:69] offset:224
	global_load_dwordx4 v[152:155], v66, s[68:69] offset:256
	global_load_dwordx4 v[156:159], v66, s[68:69] offset:288
	global_load_dwordx4 v[160:163], v66, s[68:69] offset:320
	global_load_dwordx4 v[164:167], v66, s[68:69] offset:352
	global_load_dwordx4 v[168:171], v66, s[68:69] offset:384
	global_load_dwordx4 v[172:175], v66, s[68:69] offset:416
	global_load_dwordx4 v[176:179], v66, s[68:69] offset:448
	global_load_dwordx4 v[180:183], v66, s[68:69] offset:480
	v_readlane_b32 s73, v251, 59
	v_readlane_b32 s74, v251, 60
	v_readlane_b32 s75, v251, 61
	v_readlane_b32 s76, v251, 62
	v_readlane_b32 s77, v251, 63
	v_readlane_b32 s78, v252, 0
	v_readlane_b32 s79, v252, 1
	v_readlane_b32 s80, v252, 2
	v_readlane_b32 s81, v252, 3
	v_readlane_b32 s82, v252, 4
	v_readlane_b32 s83, v252, 5
	s_waitcnt vmcnt(15)
; __device__ __forceinline__ unsigned cvt_pk_bf16(float lo, float hi) { unsigned r; asm volatile("v_cvt_pk_bf16_f32 %0, %1, %2" : "=v"(r) : "v"(lo), "v"(hi)); return r; }
; __device__ __forceinline__ void attn_unit(const bf16* Hb, const bf16* KD, const bf16* VD, bf16* MIX, int row0, int S, int head, int qb, float lam, const float* dng, float kn0, float kn1, LAS unsigned char* lds, int wave_u) {
;     ...
;         bf16* orow = MIX + (size_t)(row0 + q0 + r32e) * D + head * 128;
; #pragma unroll
;         for (int b = 0; b < 4; ++b)
; #pragma unroll
;             for (int rg = 0; rg < 4; ++rg) { const int d = 32 * b + 8 * rg + 4 * hhe; const f32x4 g4 = *(const f32x4*)(dng + d);
;                 u32x2 w; w.x = cvt_pk_bf16(o[b][4 * rg + 0] * rn * g4.x, o[b][4 * rg + 1] * rn * g4.y); w.y = cvt_pk_bf16(o[b][4 * rg + 2] * rn * g4.z, o[b][4 * rg + 3] * rn * g4.w);
;                 *(u32x2*)(orow + d) = w; }
	v_mul_f32_e32 v0, v120, v0
	v_mul_f32_e32 v2, v50, v12
	v_mul_f32_e32 v2, v121, v2
	v_cvt_pk_bf16_f32 v184, v0, v2
	v_mul_f32_e32 v0, v51, v12
	v_mul_f32_e32 v0, v122, v0
	v_mul_f32_e32 v2, v53, v12
	v_mul_f32_e32 v2, v123, v2
	v_cvt_pk_bf16_f32 v185, v0, v2
	v_lshlrev_b32_e32 v0, 3, v67
	v_lshl_add_u64 v[2:3], v[10:11], 0, v[0:1]
	v_mbcnt_lo_u32_b32 v194, -1, 0
	v_mbcnt_hi_u32_b32 v194, -1, v194
	v_and_b32_e32 v194, 32, v194
	v_lshrrev_b32_e32 v194, 2, v194
	v_mov_b32_e32 v195, 0
	v_lshl_add_u64 v[192:193], v[2:3], 0, v[194:195]
	v_mul_f32_e32 v0, v69, v12
	v_mul_f32_e32 v4, v55, v12
	v_mul_f32_e32 v5, v57, v12
	s_waitcnt vmcnt(14)
	v_mul_f32_e32 v0, v124, v0
	v_mul_f32_e32 v4, v125, v4
	v_cvt_pk_bf16_f32 v186, v0, v4
	v_mul_f32_e32 v0, v56, v12
	v_mul_f32_e32 v5, v127, v5
	v_mul_f32_e32 v0, v126, v0
	v_cvt_pk_bf16_f32 v187, v0, v5
	s_nop 1
	v_permlane32_swap_b32_e32 v184, v186
	v_permlane32_swap_b32_e32 v185, v187
	global_store_dwordx4 v[192:193], v[184:187], off
	v_mul_f32_e32 v0, v70, v12
	v_mul_f32_e32 v4, v58, v12
	v_mul_f32_e32 v5, v52, v12
	s_waitcnt vmcnt(14)
	v_mul_f32_e32 v0, v0, v128
	v_mul_f32_e32 v4, v4, v129
	v_cvt_pk_bf16_f32 v188, v0, v4
	v_mul_f32_e32 v0, v54, v12
	v_mul_f32_e32 v5, v5, v131
	v_mul_f32_e32 v0, v0, v130
	v_cvt_pk_bf16_f32 v189, v0, v5
	v_mul_f32_e32 v0, v71, v12
	v_mul_f32_e32 v4, v63, v12
	v_mul_f32_e32 v5, v61, v12
	s_waitcnt vmcnt(13)
	v_mul_f32_e32 v0, v0, v132
	v_mul_f32_e32 v4, v4, v133
	v_cvt_pk_bf16_f32 v190, v0, v4
	v_mul_f32_e32 v0, v62, v12
	v_mul_f32_e32 v5, v5, v135
	v_mul_f32_e32 v0, v0, v134
	v_cvt_pk_bf16_f32 v191, v0, v5
	s_nop 1
	v_permlane32_swap_b32_e32 v188, v190
	v_permlane32_swap_b32_e32 v189, v191
	global_store_dwordx4 v[192:193], v[188:191], off offset:32
	v_mul_f32_e32 v0, v60, v12
	v_mul_f32_e32 v4, v59, v12
	v_mul_f32_e32 v5, v34, v12
	s_waitcnt vmcnt(13)
	v_mul_f32_e32 v0, v0, v136
	v_mul_f32_e32 v4, v4, v137
	v_cvt_pk_bf16_f32 v184, v0, v4
	v_mul_f32_e32 v0, v35, v12
	v_mul_f32_e32 v5, v5, v139
	v_mul_f32_e32 v0, v0, v138
	v_cvt_pk_bf16_f32 v185, v0, v5
	v_mul_f32_e32 v0, v72, v12
	v_mul_f32_e32 v4, v65, v12
	v_mul_f32_e32 v5, v41, v12
	s_waitcnt vmcnt(12)
	v_mul_f32_e32 v0, v0, v140
	v_mul_f32_e32 v4, v4, v141
	v_cvt_pk_bf16_f32 v186, v0, v4
	v_mul_f32_e32 v0, v64, v12
	v_mul_f32_e32 v5, v5, v143
	v_mul_f32_e32 v0, v0, v142
	v_cvt_pk_bf16_f32 v187, v0, v5
	s_nop 1
	v_permlane32_swap_b32_e32 v184, v186
	v_permlane32_swap_b32_e32 v185, v187
	global_store_dwordx4 v[192:193], v[184:187], off offset:64
	v_mul_f32_e32 v0, v39, v12
	v_mul_f32_e32 v4, v38, v12
	v_mul_f32_e32 v5, v36, v12
	s_waitcnt vmcnt(12)
	v_mul_f32_e32 v0, v0, v144
	v_mul_f32_e32 v4, v4, v145
	v_cvt_pk_bf16_f32 v188, v0, v4
	v_mul_f32_e32 v0, v37, v12
	v_mul_f32_e32 v5, v5, v147
	v_mul_f32_e32 v0, v0, v146
	v_cvt_pk_bf16_f32 v189, v0, v5
	v_mul_f32_e32 v0, v73, v12
	v_mul_f32_e32 v4, v47, v12
	v_mul_f32_e32 v5, v44, v12
	s_waitcnt vmcnt(11)
	v_mul_f32_e32 v0, v0, v148
	v_mul_f32_e32 v4, v4, v149
	v_cvt_pk_bf16_f32 v190, v0, v4
	v_mul_f32_e32 v0, v45, v12
	v_mul_f32_e32 v5, v5, v151
	v_mul_f32_e32 v0, v0, v150
	v_cvt_pk_bf16_f32 v191, v0, v5
	s_nop 1
	v_permlane32_swap_b32_e32 v188, v190
	v_permlane32_swap_b32_e32 v189, v191
	global_store_dwordx4 v[192:193], v[188:191], off offset:96
	v_mul_f32_e32 v0, v43, v12
	v_mul_f32_e32 v4, v42, v12
	v_mul_f32_e32 v5, v20, v12
	s_waitcnt vmcnt(11)
	v_mul_f32_e32 v0, v0, v152
	v_mul_f32_e32 v4, v4, v153
	v_cvt_pk_bf16_f32 v184, v0, v4
	v_mul_f32_e32 v0, v40, v12
	v_mul_f32_e32 v5, v5, v155
	v_mul_f32_e32 v0, v0, v154
	v_cvt_pk_bf16_f32 v185, v0, v5
	v_mul_f32_e32 v0, v75, v12
	v_mul_f32_e32 v4, v74, v12
	v_mul_f32_e32 v5, v48, v12
	s_waitcnt vmcnt(10)
	v_mul_f32_e32 v0, v0, v156
	v_mul_f32_e32 v4, v4, v157
	v_cvt_pk_bf16_f32 v186, v0, v4
	v_mul_f32_e32 v0, v49, v12
	v_mul_f32_e32 v5, v5, v159
	v_mul_f32_e32 v0, v0, v158
	v_cvt_pk_bf16_f32 v187, v0, v5
	s_nop 1
	v_permlane32_swap_b32_e32 v184, v186
	v_permlane32_swap_b32_e32 v185, v187
	global_store_dwordx4 v[192:193], v[184:187], off offset:128
	v_mul_f32_e32 v0, v46, v12
	v_mul_f32_e32 v4, v26, v12
	v_mul_f32_e32 v5, v22, v12
	s_waitcnt vmcnt(10)
	v_mul_f32_e32 v0, v0, v160
	v_mul_f32_e32 v4, v4, v161
	v_cvt_pk_bf16_f32 v188, v0, v4
	v_mul_f32_e32 v0, v23, v12
	v_mul_f32_e32 v5, v5, v163
	v_mul_f32_e32 v0, v0, v162
	v_cvt_pk_bf16_f32 v189, v0, v5
	v_mul_f32_e32 v0, v78, v12
	v_mul_f32_e32 v4, v77, v12
	v_mul_f32_e32 v5, v33, v12
	s_waitcnt vmcnt(9)
	v_mul_f32_e32 v0, v0, v164
	v_mul_f32_e32 v4, v4, v165
	v_cvt_pk_bf16_f32 v190, v0, v4
	v_mul_f32_e32 v0, v76, v12
	v_mul_f32_e32 v5, v5, v167
	v_mul_f32_e32 v0, v0, v166
	v_cvt_pk_bf16_f32 v191, v0, v5
	s_nop 1
	v_permlane32_swap_b32_e32 v188, v190
	v_permlane32_swap_b32_e32 v189, v191
	global_store_dwordx4 v[192:193], v[188:191], off offset:160
	v_mul_f32_e32 v0, v32, v12
	v_mul_f32_e32 v4, v31, v12
	v_mul_f32_e32 v5, v27, v12
	s_waitcnt vmcnt(9)
	v_mul_f32_e32 v0, v0, v168
	v_mul_f32_e32 v4, v4, v169
	v_cvt_pk_bf16_f32 v184, v0, v4
	v_mul_f32_e32 v0, v29, v12
	v_mul_f32_e32 v5, v5, v171
	v_mul_f32_e32 v0, v0, v170
	v_cvt_pk_bf16_f32 v185, v0, v5
	v_mul_f32_e32 v0, v30, v12
	v_mul_f32_e32 v4, v28, v12
	v_mul_f32_e32 v5, v24, v12
	s_waitcnt vmcnt(8)
	v_mul_f32_e32 v0, v0, v172
	v_mul_f32_e32 v4, v4, v173
	v_cvt_pk_bf16_f32 v186, v0, v4
	v_mul_f32_e32 v0, v25, v12
	v_mul_f32_e32 v5, v5, v175
	v_mul_f32_e32 v0, v0, v174
	v_cvt_pk_bf16_f32 v187, v0, v5
	s_nop 1
	v_permlane32_swap_b32_e32 v184, v186
	v_permlane32_swap_b32_e32 v185, v187
	global_store_dwordx4 v[192:193], v[184:187], off offset:192
	v_mul_f32_e32 v0, v21, v12
	v_mul_f32_e32 v4, v19, v12
	v_mul_f32_e32 v5, v13, v12
	s_waitcnt vmcnt(8)
	v_mul_f32_e32 v0, v0, v176
	v_mul_f32_e32 v4, v4, v177
	v_cvt_pk_bf16_f32 v188, v0, v4
	v_mul_f32_e32 v0, v18, v12
	v_mul_f32_e32 v5, v5, v179
	v_mul_f32_e32 v0, v0, v178
	v_cvt_pk_bf16_f32 v189, v0, v5
	v_mul_f32_e32 v0, v8, v12
	v_mul_f32_e32 v4, v9, v12
	v_mul_f32_e32 v5, v7, v12
	s_waitcnt vmcnt(7)
	v_mul_f32_e32 v0, v0, v180
	v_mul_f32_e32 v4, v4, v181
	v_cvt_pk_bf16_f32 v190, v0, v4
	v_mul_f32_e32 v0, v6, v12
	v_mul_f32_e32 v5, v5, v183
	v_mul_f32_e32 v0, v0, v182
	v_cvt_pk_bf16_f32 v191, v0, v5
	s_nop 1
	v_permlane32_swap_b32_e32 v188, v190
	v_permlane32_swap_b32_e32 v189, v191
	global_store_dwordx4 v[192:193], v[188:191], off offset:224
	s_branch .LBB0_607
